# v45 + phase-0 x-copy loop: 4 row loads issued together with counted vmcnt instead of 4 serialized load-store round trips
# speedup vs baseline: 1.0071x; 1.0071x over previous
.LBB0_492:
	s_load_dwordx2 s[0:1], s[58:59], 0x0
	s_waitcnt lgkmcnt(0)
	v_lshl_add_u64 v[20:21], s[0:1], 0, v[8:9]
	global_load_dwordx4 v[16:19], v[20:21], off
	global_load_dwordx4 v[26:29], v[20:21], off offset:1024
	global_load_dwordx4 v[30:33], v[20:21], off offset:2048
	global_load_dwordx4 v[34:37], v[20:21], off offset:3072
	s_load_dwordx2 s[0:1], s[58:59], 0xb8
	s_waitcnt lgkmcnt(0)
	v_lshl_add_u64 v[22:23], s[0:1], 0, v[8:9]
	s_mov_b32 s0, 0x2080000
	s_waitcnt vmcnt(3)
	v_mul_f32_e32 v0, v17, v17
	v_fmac_f32_e32 v0, v16, v16
	v_fmac_f32_e32 v0, v18, v18
	v_fmac_f32_e32 v0, v19, v19
	global_store_dwordx4 v[22:23], v[16:19], off
	s_nop 1
	v_cvt_pk_bf16_f32 v16, v16, v17
	v_cvt_pk_bf16_f32 v17, v18, v19
	v_lshl_add_u64 v[18:19], s[14:15], 0, v[6:7]
	v_add_co_u32_e64 v24, s[40:41], s0, v18
	s_nop 1
	v_addc_co_u32_e64 v25, s[40:41], 0, v19, s[40:41]
	global_store_dwordx2 v[24:25], v[16:17], off
	s_waitcnt vmcnt(4)
	v_mul_f32_e32 v3, v27, v27
	v_fmac_f32_e32 v3, v26, v26
	global_store_dwordx4 v[22:23], v[26:29], off offset:1024
	v_fmac_f32_e32 v3, v28, v28
	v_fmac_f32_e32 v3, v29, v29
	v_cvt_pk_bf16_f32 v26, v26, v27
	v_cvt_pk_bf16_f32 v27, v28, v29
	global_store_dwordx2 v[24:25], v[26:27], off offset:512
	v_add_f32_e32 v0, v0, v3
	s_waitcnt vmcnt(5)
	v_mul_f32_e32 v3, v31, v31
	v_fmac_f32_e32 v3, v30, v30
	global_store_dwordx4 v[22:23], v[30:33], off offset:2048
	v_fmac_f32_e32 v3, v32, v32
	v_fmac_f32_e32 v3, v33, v33
	v_cvt_pk_bf16_f32 v30, v30, v31
	v_cvt_pk_bf16_f32 v31, v32, v33
	global_store_dwordx2 v[24:25], v[30:31], off offset:1024
	v_add_f32_e32 v0, v0, v3
	s_waitcnt vmcnt(6)
	v_mul_f32_e32 v3, v35, v35
	v_fmac_f32_e32 v3, v34, v34
	v_fmac_f32_e32 v3, v36, v36
	v_fmac_f32_e32 v3, v37, v37
	v_add_f32_e32 v0, v0, v3
	ds_bpermute_b32 v3, v10, v0
	global_store_dwordx4 v[22:23], v[34:37], off offset:3072
	s_waitcnt lgkmcnt(0)
	v_add_f32_e32 v0, v0, v3
	ds_bpermute_b32 v3, v11, v0
	v_cvt_pk_bf16_f32 v34, v34, v35
	v_cvt_pk_bf16_f32 v35, v36, v37
	global_store_dwordx2 v[24:25], v[34:35], off offset:1536
	s_waitcnt lgkmcnt(0)
	v_add_f32_e32 v0, v0, v3
	ds_bpermute_b32 v3, v12, v0
	s_waitcnt lgkmcnt(0)
	v_add_f32_e32 v0, v0, v3
	ds_bpermute_b32 v3, v13, v0
	s_waitcnt lgkmcnt(0)
	v_add_f32_e32 v0, v0, v3
	ds_bpermute_b32 v3, v14, v0
	s_waitcnt lgkmcnt(0)
	v_add_f32_e32 v0, v0, v3
	ds_bpermute_b32 v3, v15, v0
	s_and_saveexec_b64 s[6:7], vcc
	s_cbranch_execz .LBB0_491
	s_waitcnt lgkmcnt(0)
	v_add_f32_e32 v0, v0, v3
	v_cndmask_b32_e64 v0, 0, v0, s[38:39]
	v_lshl_add_u64 v[16:17], s[14:15], 0, v[4:5]
	global_store_dword v[16:17], v0, off
	s_branch .LBB0_491
